# C loop: the 8 LDS-resident q fragments cached in VGPRs per item (8 fewer ds_read_b128 per tile)
# speedup vs baseline: 1.0045x; 1.0021x over previous
; template <int OFF> DI void dsr128(bf16x8& r, int addr) { asm volatile("ds_read_b128 %0, %1 offset:%2" : "=&v"(r) : "v"(addr), "i"(OFF) : "memory"); }
; template <int DQK, int MODE>
; DI void attn_body(const AttnArgs& a, char* lds) {
;     ...
;     constexpr int NB = (KROWB == 256) ? 8 : 4;
;     int kb[NB];
;     { const int X = (hi * 16) ^ ksw(r32);
; #pragma unroll
;       for (int i = 0; i < NB; ++i) kb[i] = (int)(uintptr_t)K_lds + r32 * KROWB + ((i * 32) ^ X); }
;     const int qra = (int)(uintptr_t)qrl;
;     auto qkt = [&](f32x16& p0, f32x16& p1, const int kofs) {
;         p0 = f32x16{}; p1 = f32x16{};
;         int kc[NB];
; #pragma unroll
;         for (int i = 0; i < NB; ++i) kc[i] = kb[i] + kofs;
;         bf16x8 fk[2][2]; bf16x8 fq[2];
;         auto rd = [&](auto ic) { constexpr int d0 = decltype(ic)::value; constexpr int sl = d0 & 1;
;             dsr128<(d0 / NB) * (NB * 32)>(fk[sl][0], kc[d0 % NB]); dsr128<(d0 / NB) * (NB * 32) + 32 * KROWB>(fk[sl][1], kc[d0 % NB]);
;             if constexpr (MODE == 2 && d0 >= NQR) dsr128<(d0 - NQR) * 1024>(fq[sl], qra); };
.Lprio_skip_2:
	s_or_b64 exec, exec, s[10:11]
	ds_read_b128 v[194:197], v139
	ds_read_b128 v[198:201], v139 offset:1024
	ds_read_b128 v[202:205], v139 offset:2048
	ds_read_b128 v[206:209], v139 offset:3072
	ds_read_b128 v[210:213], v139 offset:4096
	ds_read_b128 v[214:217], v139 offset:5120
	ds_read_b128 v[228:231], v139 offset:6144
	ds_read_b128 v[232:235], v139 offset:7168
	s_waitcnt lgkmcnt(0)
	v_subrev_u32_e32 v220, s14, v116
	v_subrev_u32_e32 v221, s14, v120
	v_subrev_u32_e32 v222, s14, v124
	v_lshlrev_b32_e32 v223, 7, v118
	v_lshlrev_b32_e32 v224, 7, v122
	v_lshlrev_b32_e32 v225, 7, v126
	v_subrev_u32_e32 v226, s14, v128
	v_subrev_u32_e32 v227, s14, v130
	v_add_u32_e32 v220, v220, v223
	v_add_u32_e32 v221, v221, v224
	v_add_u32_e32 v222, v222, v225
	v_add_u32_e32 v226, 0x100, v226
	v_add_u32_e32 v227, 0x100, v227
	s_add_u32 s89, s14, 0x40000
	s_addc_u32 s90, s12, 0
	s_cmp_lt_u32 s16, 0x1000
	s_cbranch_scc0 .Lstg_c_pro
	s_barrier

; #define SBAR() __builtin_amdgcn_sched_barrier(0)
; template <int I, int N, class F> DI void cfor(F&& f) { if constexpr (I < N) { f(std::integral_constant<int, I>{}); cfor<I + 1, N>(f); } }
; template <int OFF> DI void dsr128(bf16x8& r, int addr) { asm volatile("ds_read_b128 %0, %1 offset:%2" : "=&v"(r) : "v"(addr), "i"(OFF) : "memory"); }
; template <int DQK, int MODE>
; DI void attn_body(const AttnArgs& a, char* lds) {
;     ...
;     auto qkt = [&](f32x16& p0, f32x16& p1, const int kofs) {
;         p0 = f32x16{}; p1 = f32x16{};
;         int kc[NB];
; #pragma unroll
;         for (int i = 0; i < NB; ++i) kc[i] = kb[i] + kofs;
;         bf16x8 fk[2][2]; bf16x8 fq[2];
;         auto rd = [&](auto ic) { constexpr int d0 = decltype(ic)::value; constexpr int sl = d0 & 1;
;             dsr128<(d0 / NB) * (NB * 32)>(fk[sl][0], kc[d0 % NB]); dsr128<(d0 / NB) * (NB * 32) + 32 * KROWB>(fk[sl][1], kc[d0 % NB]);
;             if constexpr (MODE == 2 && d0 >= NQR) dsr128<(d0 - NQR) * 1024>(fq[sl], qra); };
;         rd(std::integral_constant<int, 0>{});
;         cfor<0, ND0>([&](auto ic) { constexpr int d0 = decltype(ic)::value; constexpr int sl = d0 & 1;
;             if constexpr (d0 + 1 < ND0) { rd(std::integral_constant<int, d0 + 1>{}); wait_lgkm<(MODE == 2 && d0 + 1 >= NQR) ? 3 : 2>(); }
;             else wait_lgkm<0>();
;             SBAR();
;             bf16x8 qf; if constexpr (MODE == 2 && d0 >= NQR) qf = fq[sl]; else qf = qr[d0 < NQR ? d0 : 0];
;             p0 = __builtin_amdgcn_mfma_f32_32x32x16_bf16(fk[sl][0], qf, p0, 0, 0, 0);
;             p1 = __builtin_amdgcn_mfma_f32_32x32x16_bf16(fk[sl][1], qf, p1, 0, 0, 0); });
;     ...
;             float pmax = p0[0];
; #pragma unroll
;             for (int r = 1; r < 16; ++r) pmax = fmaxf(pmax, p0[r]);
; #pragma unroll
;             for (int r = 0; r < 16; ++r) pmax = fmaxf(pmax, p1[r]);
;             { auto rr = __builtin_amdgcn_permlane32_swap(__float_as_uint(pmax), __float_as_uint(pmax), false, false);
;               pmax = fmaxf(__uint_as_float(rr[0]), __uint_as_float(rr[1])); }
;             if (__builtin_expect(__all((pmax - m_reg) * C <= THR_L2), 1)) { mn = m_reg; alpha = 1.f; }
;             else { mn = fmaxf(m_reg, pmax); alpha = __builtin_amdgcn_exp2f((m_reg - mn) * C); m_reg = mn; }
;             const float mnC = -mn * C;
.Lstg_c_nok:
	s_mul_i32 s10, s35, 0x6000
	v_add_u32_e32 v0, s10, v119
	ds_read_b128 v[66:69], v0 offset:0
	ds_read_b128 v[70:73], v0 offset:0x3000
	v_add_u32_e32 v145, s10, v123
	ds_read_b128 v[146:149], v145 offset:0
	ds_read_b128 v[150:153], v145 offset:0x3000
	s_waitcnt lgkmcnt(2)
	v_add_u32_e32 v170, s10, v127
	v_add_u32_e32 v171, s10, v140
	v_mfma_f32_32x32x16_bf16 v[82:97], v[66:69], v[98:101], 0
	ds_read_b128 v[154:157], v170 offset:0
	ds_read_b128 v[158:161], v170 offset:0x3000
	s_waitcnt lgkmcnt(2)
	v_mfma_f32_32x32x16_bf16 v[66:81], v[70:73], v[98:101], 0
	v_mfma_f32_32x32x16_bf16 v[82:97], v[146:149], v[102:105], v[82:97]
	ds_read_b128 v[146:149], v171 offset:0
	v_mfma_f32_32x32x16_bf16 v[66:81], v[150:153], v[102:105], v[66:81]
	ds_read_b128 v[150:153], v171 offset:0x3000
	s_waitcnt lgkmcnt(2)
	v_mfma_f32_32x32x16_bf16 v[82:97], v[154:157], v[106:109], v[82:97]
	ds_read_b128 v[154:157], v0 offset:0x80
	v_mfma_f32_32x32x16_bf16 v[66:81], v[158:161], v[106:109], v[66:81]
	ds_read_b128 v[158:161], v0 offset:0x3080
	s_waitcnt lgkmcnt(2)
	v_mfma_f32_32x32x16_bf16 v[82:97], v[146:149], v[110:113], v[82:97]
	ds_read_b128 v[146:149], v145 offset:0x80
	v_mfma_f32_32x32x16_bf16 v[66:81], v[150:153], v[110:113], v[66:81]
	ds_read_b128 v[150:153], v145 offset:0x3080
	s_waitcnt lgkmcnt(2)
	v_mfma_f32_32x32x16_bf16 v[82:97], v[154:157], v[194:197], v[82:97]
	ds_read_b128 v[154:157], v170 offset:0x80
	v_mfma_f32_32x32x16_bf16 v[66:81], v[158:161], v[194:197], v[66:81]
	ds_read_b128 v[158:161], v170 offset:0x3080
	s_waitcnt lgkmcnt(2)
	v_mfma_f32_32x32x16_bf16 v[82:97], v[146:149], v[198:201], v[82:97]
	ds_read_b128 v[146:149], v171 offset:0x80
	v_mfma_f32_32x32x16_bf16 v[66:81], v[150:153], v[198:201], v[66:81]
	ds_read_b128 v[150:153], v171 offset:0x3080
	s_waitcnt lgkmcnt(2)
	v_mfma_f32_32x32x16_bf16 v[82:97], v[154:157], v[202:205], v[82:97]
	ds_read_b128 v[154:157], v0 offset:0x100
	v_mfma_f32_32x32x16_bf16 v[66:81], v[158:161], v[202:205], v[66:81]
	ds_read_b128 v[158:161], v0 offset:0x3100
	s_waitcnt lgkmcnt(2)
	v_mfma_f32_32x32x16_bf16 v[82:97], v[146:149], v[206:209], v[82:97]
	ds_read_b128 v[146:149], v145 offset:0x100
	v_mfma_f32_32x32x16_bf16 v[66:81], v[150:153], v[206:209], v[66:81]
	ds_read_b128 v[150:153], v145 offset:0x3100
	s_waitcnt lgkmcnt(2)
	v_mfma_f32_32x32x16_bf16 v[82:97], v[154:157], v[210:213], v[82:97]
	ds_read_b128 v[154:157], v170 offset:0x100
	v_mfma_f32_32x32x16_bf16 v[66:81], v[158:161], v[210:213], v[66:81]
	ds_read_b128 v[158:161], v170 offset:0x3100
	s_waitcnt lgkmcnt(2)
	v_mfma_f32_32x32x16_bf16 v[82:97], v[146:149], v[214:217], v[82:97]
	ds_read_b128 v[146:149], v171 offset:0x100
	v_mfma_f32_32x32x16_bf16 v[66:81], v[150:153], v[214:217], v[66:81]
	ds_read_b128 v[150:153], v171 offset:0x3100
	s_waitcnt lgkmcnt(2)
	v_mfma_f32_32x32x16_bf16 v[82:97], v[154:157], v[228:231], v[82:97]
	s_waitcnt lgkmcnt(0)
	v_mfma_f32_32x32x16_bf16 v[66:81], v[158:161], v[228:231], v[66:81]
	v_mfma_f32_32x32x16_bf16 v[82:97], v[146:149], v[232:235], v[82:97]
	v_mfma_f32_32x32x16_bf16 v[66:81], v[150:153], v[232:235], v[66:81]
	s_nop 9
	v_max_f32_e32 v145, v82, v83
	v_max3_f32 v145, v145, v84, v85
	v_max3_f32 v145, v145, v86, v87
	v_max3_f32 v145, v145, v88, v89
	v_max3_f32 v145, v145, v90, v91
	v_max3_f32 v145, v145, v92, v93
	v_max3_f32 v145, v145, v94, v95
	v_max3_f32 v145, v145, v96, v97
	v_max3_f32 v145, v145, v66, v67
	v_max3_f32 v145, v145, v68, v69
	v_max3_f32 v145, v145, v70, v71
	v_max3_f32 v145, v145, v72, v73
	v_max3_f32 v145, v145, v74, v75
	v_max3_f32 v145, v145, v76, v77
	v_max3_f32 v145, v145, v78, v79
	v_max3_f32 v145, v145, v80, v81
	v_mov_b32_e32 v146, v145
	s_nop 1
	v_permlane32_swap_b32_e32 v145, v146
	v_max_f32_e32 v145, v145, v146
	v_sub_f32_e32 v146, v145, v143
	v_cmp_ge_f32_e32 vcc, 0x42ddb3d8, v146
	s_mov_b32 s32, 0
	s_cmp_eq_u64 vcc, exec
	s_cbranch_scc1 .Ltrim_c_fast
	v_max_f32_e32 v0, v143, v145
	v_sub_f32_e32 v146, v143, v0
	v_mul_f32_e32 v146, 0x3dd53b94, v146
	v_exp_f32_e32 v146, v146
	v_mov_b32_e32 v143, v0
	v_mul_f32_e32 v241, 0xbdd53b94, v143
	v_mov_b32_e32 v0, v146
	s_mov_b32 s32, 1
